# layer 1: 40 w_out GEMM tiles run in the tail of the dual projection GEMM (per-workgroup release, single-wave poll); P5 tile order rows 0-31 then 32-36
# speedup vs baseline: 1.0316x; 1.0316x over previous
;     __device__ bool next(int i, Unit& u) const {
;     ...
;         if (i == 2 && c < 80) { StaticOrder t = *this; t.c = c < 40 ? c : c - 40; if (!t.next(1, u)) return false; u.mode = c < 40 ? 2 : 3; return true; }
; __device__ __forceinline__ void run_phase(const Params& p, int ph, LAS unsigned char* lds, const int tid, const int bid) {
;     ...
;         { const int sidx = bid < 40 ? bid : (bid < 80 ? bid - 40 : 0); E.m1 = (float*)(pws(p) + OFF_M1) + ((size_t)l * 40 + sidx) * 65536; E.flag = (unsigned*)(pws(p) + OFF_BAR + 16384) + (l * 40 + sidx) * 64; }
.LBB0_146:
	s_sub_i32 s1, s82, 40
	s_cmpk_lt_i32 s82, 0x50
	s_cselect_b64 s[12:13], -1, 0
	s_and_b64 s[14:15], s[12:13], exec
	s_cselect_b32 s8, s1, 0
	s_cmp_lt_i32 s82, 40
	s_cselect_b32 s8, s82, s8
	s_mul_i32 s14, s16, 40
	s_cselect_b32 s1, s82, s1
	s_cselect_b32 s79, 2, 3
	s_ashr_i32 s15, s8, 31
	s_mul_hi_u32 s11, s16, 40
	s_add_u32 s14, s14, s8
	s_addc_u32 s15, s11, s15
	s_lshl_b64 s[14:15], s[14:15], 18
	v_readlane_b32 s11, v253, 21
	s_mov_b32 s18, s16
	s_mul_i32 s16, s16, 40
	s_add_u32 s11, s11, s14
	v_readlane_b32 s14, v253, 22
	s_addc_u32 s20, s14, s15
	s_add_i32 s8, s8, s16
	s_lshl_b32 s14, s8, 6
	s_ashr_i32 s15, s14, 31
	s_lshl_b64 s[14:15], s[14:15], 2
	v_readlane_b32 s8, v253, 23
	v_bfe_u32 v16, v244, 4, 2
	s_add_u32 s14, s8, s14
	v_readlane_b32 s8, v253, 24
	v_and_b32_e32 v15, 15, v244
	v_lshlrev_b32_e32 v18, 4, v16
	v_lshlrev_b32_e32 v19, 2, v244
	s_addc_u32 s15, s8, s15
	v_lshl_or_b32 v18, v15, 6, v18
	s_and_b32 s6, s6, 3
	s_lshl_b32 s8, s7, 13
	v_and_b32_e32 v19, 32, v19
	s_add_i32 m0, s36, 0x18000
	v_lshl_add_u64 v[8:9], v[8:9], 0, s[92:93]
	v_bitop3_b32 v20, v18, s8, v19 bitop3:0xde
	s_lshl_b32 s8, s6, 12
	s_waitcnt vmcnt(4)
	s_barrier
	global_load_lds_dwordx4 v[8:9], off
	v_lshl_add_u64 v[6:7], v[6:7], 0, s[92:93]
	s_add_i32 m0, s36, 0x1a000
	s_add_i32 s41, s36, 0x8000
	s_add_i32 s83, s36, 0xa000
	global_load_lds_dwordx4 v[6:7], off
	v_lshl_add_u64 v[4:5], v[4:5], 0, s[92:93]
	s_mov_b32 m0, s41
	s_add_u32 s16, s24, 0x80080
	global_load_lds_dwordx4 v[4:5], off
	v_lshl_add_u64 v[2:3], v[2:3], 0, s[92:93]
	s_mov_b32 m0, s83
	s_addc_u32 s17, s25, 0
	global_load_lds_dwordx4 v[2:3], off
	s_add_i32 m0, s36, 0x1c000
	v_lshl_add_u64 v[2:3], s[16:17], 0, v[178:179]
	global_load_lds_dwordx4 v[2:3], off
	v_lshl_add_u64 v[2:3], s[16:17], 0, v[182:183]
	s_add_i32 m0, s36, 0x1e000
	v_lshl_or_b32 v197, s7, 6, v15
	global_load_lds_dwordx4 v[2:3], off
	s_lshl_b32 s7, s7, 2
	v_writelane_b32 v254, s18, 46
	s_or_b32 s16, s7, s6
	s_ashr_i32 s17, s16, 31
	v_writelane_b32 v254, s19, 47
	v_bitop3_b32 v245, s8, v18, v19 bitop3:0xf6
	s_lshl_b64 s[16:17], s[16:17], 15
	s_ashr_i32 s8, s1, 31
	v_readlane_b32 s18, v254, 24
	s_add_u32 s18, s1, s18
	v_readlane_b32 s1, v253, 25
	s_addc_u32 s19, s8, s1
	s_ashr_i32 s1, s18, 31
	s_lshr_b32 s1, s1, 29
	s_add_i32 s1, s18, s1
	s_ashr_i32 s8, s1, 3
	s_and_b32 s1, s1, -8
	v_cmp_lt_i64_e64 s[86:87], s[18:19], v[248:249]
	s_sub_i32 s1, s18, s1
	s_ashr_i32 s18, s82, 31
	s_lshr_b32 s18, s18, 29
	s_add_i32 s18, s82, s18
	s_ashr_i32 s19, s18, 3
	s_and_b32 s18, s18, -8
	s_sub_i32 s18, s82, s18
	s_add_u32 s16, s11, s16
	s_addc_u32 s17, s20, s17
	s_cmp_lt_i32 s1, 0
	s_cselect_b32 s11, 38, 37
	s_mul_i32 s1, s11, s1
	s_add_i32 s1, s1, s8
	s_cmpk_lg_u32 s42, 0x100
	s_cbranch_scc1 .Lp5_r2map_done
	s_sub_i32 s11, s82, 40
	s_cmp_lt_i32 s82, 40
	s_cselect_b32 s11, s82, s11
	s_and_b32 s8, s11, 7
	s_mul_i32 s8, s8, 5
	s_lshr_b32 s11, s11, 3
	s_add_i32 s1, s8, s11
	s_addk_i32 s1, 0x100

;     __device__ __forceinline__ bool operator()(f32x4 (&acc)[2][2][4][2], const Unit& un, int wr, int wc, int fr, int fq) const {
;     ...
;             asm volatile("s_waitcnt vmcnt(0)" ::: "memory");
;             __builtin_amdgcn_fence(__ATOMIC_RELEASE, "agent");
;             asm volatile("s_waitcnt vmcnt(0)" ::: "memory");
;             if (fr == 0 && fq == 0) __hip_atomic_fetch_add(flag, 1u, __ATOMIC_RELAXED, __HIP_MEMORY_SCOPE_AGENT);
.LBB0_148:
	s_cmp_eq_u32 s81, 11
	s_cbranch_scc0 .Lp5_nosig
	s_cmp_eq_u32 s85, 2
	s_cbranch_scc0 .Lp5_nosig
	s_cmpk_lg_u32 s42, 0x100
	s_cbranch_scc1 .Lp5_nosig
	s_and_b32 s22, s82, 7
	s_cmp_lt_u32 s22, 6
	s_cbranch_scc1 .Lp5_nosig
	s_waitcnt vmcnt(0)
	s_barrier
	s_barrier
	s_cmpk_gt_u32 s63, 0x3f
	s_cbranch_scc1 .Lp5_nosig
	v_readlane_b32 s22, v253, 23
	v_readlane_b32 s23, v253, 24
	buffer_wbl2 sc1
	s_waitcnt vmcnt(0)
	s_add_u32 s22, s22, 0x6000
	s_addc_u32 s23, s23, 0
	s_mov_b64 vcc, exec
	s_mov_b64 exec, 1
	s_nop 4
	global_atomic_add v1, v236, s[22:23]
	s_mov_b64 exec, vcc

;     __device__ __forceinline__ bool operator()(f32x4 (&acc)[2][2][4][2], const Unit& un, int wr, int wc, int fr, int fq) const {
;     ...
;             while (__hip_atomic_load(flag, __ATOMIC_RELAXED, __HIP_MEMORY_SCOPE_AGENT) < 8u) { __builtin_amdgcn_s_sleep(2); if (++sp > (1u << 22)) break; }
;             __builtin_amdgcn_fence(__ATOMIC_ACQUIRE, "agent");
;             asm volatile("s_waitcnt vmcnt(0)" ::: "memory");
.LBB0_262:
	s_cmp_eq_u32 s81, 11
	s_cbranch_scc0 .Lp5_noshadow
	s_cmpk_lg_u32 s42, 0x100
	s_cbranch_scc1 .Lp5_noshadow
	s_cmpk_lt_u32 s82, 0x50
	s_cbranch_scc1 .Lp5_noshadow
	s_cmpk_gt_u32 s82, 0x77
	s_cbranch_scc1 .Lp5_noshadow
	s_cmpk_gt_u32 s63, 0x3f
	s_cbranch_scc1 .Lp5_spun
	v_readlane_b32 s6, v253, 23
	v_readlane_b32 s7, v253, 24
	s_movk_i32 s8, 0x4000
	s_add_u32 s6, s6, 0x6000
	s_addc_u32 s7, s7, 0
	s_nop 4
.Lp5_spin:
	global_load_dword v2, v1, s[6:7] sc1
	s_waitcnt vmcnt(0)
	v_readfirstlane_b32 s9, v2
	s_nop 0
	s_cmpk_ge_u32 s9, 0x40
	s_cbranch_scc1 .Lp5_spun
	s_sleep 2
	s_sub_i32 s8, s8, 1
	s_cmp_lg_u32 s8, 0
	s_cbranch_scc1 .Lp5_spin
.Lp5_spun:
	s_barrier
	buffer_inv sc1
	s_waitcnt vmcnt(0)
	s_add_i32 s8, s82, 0xffffffb1
	s_nop 0
	v_writelane_b32 v255, s8, 5
	s_branch .Lp6_entry
